# instruction selection: SwiGLU epilogue with scalar v_mul/v_fma pairs instead of packed v_pk_mul/v_pk_fma (testing whether packed f32 is the slower form here)
# speedup vs baseline: 1.0047x; 1.0047x over previous
; __device__ __forceinline__ float silu_f(float x) { return x * __builtin_amdgcn_rcpf(1.0f + __builtin_amdgcn_exp2f(-1.4426950408889634f * x)); }
;     __device__ __forceinline__ void operator()(const i32x4 (&acc)[2][2][4][2], const pg8::Unit& u, int wr, int wc, int fr_, int fq_, int tid) {
;         int fr = fr_, fq = fq_; asm volatile("" : "+v"(fr), "+v"(fq));
;         if (skip) return;
;         const int row0 = u.pm * 256 + wr * 64 + fr, col0 = u.pn * 128 + wc * 32 + 8 * fq;
;         const float* cp = cmax + u.pn * 256 + wc * 32 + 8 * fq;
;         f32x4 cs[2][2];
;         cs[0][0] = *(const f32x4*)(cp) * (1.0f / 127.0f); cs[0][1] = *(const f32x4*)(cp + 4) * (1.0f / 127.0f);
;         cs[1][0] = *(const f32x4*)(cp + 128) * (1.0f / 127.0f); cs[1][1] = *(const f32x4*)(cp + 132) * (1.0f / 127.0f);
; #pragma unroll
;         for (int ai = 0; ai < 2; ++ai)
; #pragma unroll
;             for (int m = 0; m < 4; ++m) {
;                 const int row = row0 + ai * 128 + m * 16;
;                 const float rs = rsl[wr * 64 + fr + ai * 128 + m * 16];
;                 f32x4 h[2];
; #pragma unroll
;                 for (int n = 0; n < 2; ++n) {
; #pragma unroll
;                     for (int i = 0; i < 4; ++i) { const float g = (float)acc[ai][0][m][n][i] * (rs * cs[0][n][i]), up = (float)acc[ai][1][m][n][i] * (rs * cs[1][n][i]); h[n][i] = silu_f(g) * up; } }
;                 *(u32x4*)(H + ((size_t)(u.pm * (DFF / 64) + (col0 >> 6)) * 256 + (size_t)(row & 255)) * 64 + (col0 & 63)) = pack8bf(h[0], h[1]);
;             }
.LBB0_166:
	s_mul_i32 s13, s20, 0x58
	v_lshrrev_b32_e32 v175, 4, v195
	v_and_b32_e32 v174, 15, v195
	s_lshr_b32 s22, s21, 2
	s_lshl_b32 s22, s22, 10
	s_lshl_b32 s23, s41, 3
	s_add_i32 s22, s22, s23
	s_add_i32 s22, s22, 0x21000
	v_lshlrev_b32_e32 v176, 4, v175
	v_lshl_add_u32 v175, v175, 5, s22
	ds_read_b128 v[216:219], v175
	ds_read_b128 v[220:223], v175 offset:16
	ds_read_b128 v[224:227], v175 offset:128
	ds_read_b128 v[228:231], v175 offset:144
	v_add_u32_e32 v177, s40, v174
	v_lshl_add_u32 v174, v174, 2, s47
	ds_read_b32 v232, v174
	ds_read_b32 v234, v174 offset:64
	ds_read_b32 v236, v174 offset:128
	ds_read_b32 v238, v174 offset:192
	ds_read_b32 v240, v174 offset:512
	ds_read_b32 v242, v174 offset:576
	ds_read_b32 v244, v174 offset:640
	ds_read_b32 v246, v174 offset:704
	v_lshl_add_u32 v176, v177, 7, v176
	s_lshl_b32 s22, s21, 1
	s_add_i32 s13, s13, s22
	s_lshr_b32 s22, s41, 6
	s_add_i32 s13, s13, s22
	s_and_b32 s22, s41, 32
	s_lshl_b32 s22, s22, 1
	v_add_u32_e32 v176, s22, v176
	s_lshl_b32 s13, s13, 15
	s_add_u32 s20, s8, s13
	s_addc_u32 s21, s9, 0
	v_cvt_f32_i32_e32 v126, v126
	v_cvt_f32_i32_e32 v127, v127
	v_cvt_f32_i32_e32 v128, v128
	v_cvt_f32_i32_e32 v129, v129
	v_cvt_f32_i32_e32 v122, v122
	v_cvt_f32_i32_e32 v123, v123
	v_cvt_f32_i32_e32 v124, v124
	v_cvt_f32_i32_e32 v125, v125
	v_cvt_f32_i32_e32 v118, v118
	v_cvt_f32_i32_e32 v119, v119
	v_cvt_f32_i32_e32 v120, v120
	v_cvt_f32_i32_e32 v121, v121
	v_cvt_f32_i32_e32 v114, v114
	v_cvt_f32_i32_e32 v115, v115
	v_cvt_f32_i32_e32 v116, v116
	v_cvt_f32_i32_e32 v117, v117
	v_cvt_f32_i32_e32 v110, v110
	v_cvt_f32_i32_e32 v111, v111
	v_cvt_f32_i32_e32 v112, v112
	v_cvt_f32_i32_e32 v113, v113
	v_cvt_f32_i32_e32 v106, v106
	v_cvt_f32_i32_e32 v107, v107
	v_cvt_f32_i32_e32 v108, v108
	v_cvt_f32_i32_e32 v109, v109
	v_cvt_f32_i32_e32 v102, v102
	v_cvt_f32_i32_e32 v103, v103
	v_cvt_f32_i32_e32 v104, v104
	v_cvt_f32_i32_e32 v105, v105
	v_cvt_f32_i32_e32 v98, v98
	v_cvt_f32_i32_e32 v99, v99
	v_cvt_f32_i32_e32 v100, v100
	v_cvt_f32_i32_e32 v101, v101
	s_waitcnt lgkmcnt(0)
	v_mul_f32_e32 v233, v232, v232
	v_mul_f32_e32 v235, v234, v234
	v_mul_f32_e32 v237, v236, v236
	v_mul_f32_e32 v239, v238, v238
	v_mul_f32_e32 v241, v240, v240
	v_mul_f32_e32 v243, v242, v242
	v_mul_f32_e32 v245, v244, v244
	v_mul_f32_e32 v247, v246, v246
	v_rcp_f32_e32 v233, v233
	v_rcp_f32_e32 v235, v235
	v_rcp_f32_e32 v237, v237
	v_rcp_f32_e32 v239, v239
	v_rcp_f32_e32 v241, v241
	v_rcp_f32_e32 v243, v243
	v_rcp_f32_e32 v245, v245
	v_rcp_f32_e32 v247, v247
	v_mul_f32_e32 v232, 0xbfb8aa3b, v232
	v_mul_f32_e32 v234, 0xbfb8aa3b, v234
	v_mul_f32_e32 v236, 0xbfb8aa3b, v236
	v_mul_f32_e32 v238, 0xbfb8aa3b, v238
	v_mul_f32_e32 v240, 0xbfb8aa3b, v240
	v_mul_f32_e32 v242, 0xbfb8aa3b, v242
	v_mul_f32_e32 v244, 0xbfb8aa3b, v244
	v_mul_f32_e32 v246, 0xbfb8aa3b, v246
	v_cvt_f32_i32_e32 v94, v94
	v_cvt_f32_i32_e32 v95, v95
	v_cvt_f32_i32_e32 v96, v96
	v_cvt_f32_i32_e32 v97, v97
	v_cvt_f32_i32_e32 v90, v90
	v_cvt_f32_i32_e32 v91, v91
	v_cvt_f32_i32_e32 v92, v92
	v_cvt_f32_i32_e32 v93, v93
	v_cvt_f32_i32_e32 v86, v86
	v_cvt_f32_i32_e32 v87, v87
	v_cvt_f32_i32_e32 v88, v88
	v_cvt_f32_i32_e32 v89, v89
	v_cvt_f32_i32_e32 v82, v82
	v_cvt_f32_i32_e32 v83, v83
	v_cvt_f32_i32_e32 v84, v84
	v_cvt_f32_i32_e32 v85, v85
	v_mul_f32_e32 v126, v126, v216
	v_mul_f32_e32 v127, v127, v217
	v_mul_f32_e32 v128, v128, v218
	v_mul_f32_e32 v129, v129, v219
	v_mul_f32_e32 v122, v122, v224
	v_mul_f32_e32 v123, v123, v225
	v_mul_f32_e32 v124, v124, v226
	v_mul_f32_e32 v125, v125, v227
	v_mul_f32_e32 v248, v126, v232
	v_mul_f32_e32 v249, v127, v232
	v_mul_f32_e32 v250, v128, v232
	v_mul_f32_e32 v251, v129, v232
	v_exp_f32_e32 v248, v248
	v_exp_f32_e32 v249, v249
	v_exp_f32_e32 v250, v250
	v_exp_f32_e32 v251, v251
	v_mul_f32_e32 v126, v126, v122
	v_mul_f32_e32 v127, v127, v123
	v_mul_f32_e32 v128, v128, v124
	v_mul_f32_e32 v129, v129, v125
	v_fma_f32 v248, v248, v233, v233
	v_fma_f32 v249, v249, v233, v233
	v_fma_f32 v250, v250, v233, v233
	v_fma_f32 v251, v251, v233, v233
	v_rcp_f32_e32 v248, v248
	v_rcp_f32_e32 v249, v249
	v_rcp_f32_e32 v250, v250
	v_rcp_f32_e32 v251, v251
	v_mul_f32_e32 v126, v126, v248
	v_mul_f32_e32 v127, v127, v249
	v_mul_f32_e32 v128, v128, v250
	v_mul_f32_e32 v129, v129, v251
	v_cvt_pk_bf16_f32 v122, v126, v127
	v_cvt_pk_bf16_f32 v123, v128, v129
	v_mul_f32_e32 v118, v118, v220
	v_mul_f32_e32 v119, v119, v221
	v_mul_f32_e32 v120, v120, v222
	v_mul_f32_e32 v121, v121, v223
	v_mul_f32_e32 v114, v114, v228
	v_mul_f32_e32 v115, v115, v229
	v_mul_f32_e32 v116, v116, v230
	v_mul_f32_e32 v117, v117, v231
	v_mul_f32_e32 v248, v118, v232
	v_mul_f32_e32 v249, v119, v232
	v_mul_f32_e32 v250, v120, v232
	v_mul_f32_e32 v251, v121, v232
	v_exp_f32_e32 v248, v248
	v_exp_f32_e32 v249, v249
	v_exp_f32_e32 v250, v250
	v_exp_f32_e32 v251, v251
	v_mul_f32_e32 v118, v118, v114
	v_mul_f32_e32 v119, v119, v115
	v_mul_f32_e32 v120, v120, v116
	v_mul_f32_e32 v121, v121, v117
	v_fma_f32 v248, v248, v233, v233
	v_fma_f32 v249, v249, v233, v233
	v_fma_f32 v250, v250, v233, v233
	v_fma_f32 v251, v251, v233, v233
	v_rcp_f32_e32 v248, v248
	v_rcp_f32_e32 v249, v249
	v_rcp_f32_e32 v250, v250
	v_rcp_f32_e32 v251, v251
	v_mul_f32_e32 v118, v118, v248
	v_mul_f32_e32 v119, v119, v249
	v_mul_f32_e32 v120, v120, v250
	v_mul_f32_e32 v121, v121, v251
	v_cvt_pk_bf16_f32 v124, v118, v119
	v_cvt_pk_bf16_f32 v125, v120, v121
	s_mov_b64 s[22:23], s[20:21]
	global_store_dwordx4 v176, v[122:125], s[22:23] sc1
	v_cvt_f32_i32_e32 v78, v78
	v_cvt_f32_i32_e32 v79, v79
	v_cvt_f32_i32_e32 v80, v80
	v_cvt_f32_i32_e32 v81, v81
	v_cvt_f32_i32_e32 v74, v74
	v_cvt_f32_i32_e32 v75, v75
; __device__ __forceinline__ float silu_f(float x) { return x * __builtin_amdgcn_rcpf(1.0f + __builtin_amdgcn_exp2f(-1.4426950408889634f * x)); }
;     __device__ __forceinline__ void operator()(const i32x4 (&acc)[2][2][4][2], const pg8::Unit& u, int wr, int wc, int fr_, int fq_, int tid) {
;     ...
;         for (int ai = 0; ai < 2; ++ai)
; #pragma unroll
;             for (int m = 0; m < 4; ++m) {
;                 const int row = row0 + ai * 128 + m * 16;
;                 const float rs = rsl[wr * 64 + fr + ai * 128 + m * 16];
;                 f32x4 h[2];
; #pragma unroll
;                 for (int n = 0; n < 2; ++n) {
; #pragma unroll
;                     for (int i = 0; i < 4; ++i) { const float g = (float)acc[ai][0][m][n][i] * (rs * cs[0][n][i]), up = (float)acc[ai][1][m][n][i] * (rs * cs[1][n][i]); h[n][i] = silu_f(g) * up; } }
;                 *(u32x4*)(H + ((size_t)(u.pm * (DFF / 64) + (col0 >> 6)) * 256 + (size_t)(row & 255)) * 64 + (col0 & 63)) = pack8bf(h[0], h[1]);
;             }
	v_cvt_f32_i32_e32 v76, v76
	v_cvt_f32_i32_e32 v77, v77
	v_cvt_f32_i32_e32 v70, v70
	v_cvt_f32_i32_e32 v71, v71
	v_cvt_f32_i32_e32 v72, v72
	v_cvt_f32_i32_e32 v73, v73
	v_cvt_f32_i32_e32 v66, v66
	v_cvt_f32_i32_e32 v67, v67
	v_cvt_f32_i32_e32 v68, v68
	v_cvt_f32_i32_e32 v69, v69
	v_mul_f32_e32 v110, v110, v216
	v_mul_f32_e32 v111, v111, v217
	v_mul_f32_e32 v112, v112, v218
	v_mul_f32_e32 v113, v113, v219
	v_mul_f32_e32 v106, v106, v224
	v_mul_f32_e32 v107, v107, v225
	v_mul_f32_e32 v108, v108, v226
	v_mul_f32_e32 v109, v109, v227
	v_mul_f32_e32 v248, v110, v234
	v_mul_f32_e32 v249, v111, v234
	v_mul_f32_e32 v250, v112, v234
	v_mul_f32_e32 v251, v113, v234
	v_exp_f32_e32 v248, v248
	v_exp_f32_e32 v249, v249
	v_exp_f32_e32 v250, v250
	v_exp_f32_e32 v251, v251
	v_mul_f32_e32 v110, v110, v106
	v_mul_f32_e32 v111, v111, v107
	v_mul_f32_e32 v112, v112, v108
	v_mul_f32_e32 v113, v113, v109
	v_fma_f32 v248, v248, v235, v235
	v_fma_f32 v249, v249, v235, v235
	v_fma_f32 v250, v250, v235, v235
	v_fma_f32 v251, v251, v235, v235
	v_rcp_f32_e32 v248, v248
	v_rcp_f32_e32 v249, v249
	v_rcp_f32_e32 v250, v250
	v_rcp_f32_e32 v251, v251
	v_mul_f32_e32 v110, v110, v248
	v_mul_f32_e32 v111, v111, v249
	v_mul_f32_e32 v112, v112, v250
	v_mul_f32_e32 v113, v113, v251
	v_cvt_pk_bf16_f32 v106, v110, v111
	v_cvt_pk_bf16_f32 v107, v112, v113
	v_mul_f32_e32 v102, v102, v220
	v_mul_f32_e32 v103, v103, v221
	v_mul_f32_e32 v104, v104, v222
	v_mul_f32_e32 v105, v105, v223
	v_mul_f32_e32 v98, v98, v228
	v_mul_f32_e32 v99, v99, v229
	v_mul_f32_e32 v100, v100, v230
	v_mul_f32_e32 v101, v101, v231
	v_mul_f32_e32 v248, v102, v234
	v_mul_f32_e32 v249, v103, v234
	v_mul_f32_e32 v250, v104, v234
	v_mul_f32_e32 v251, v105, v234
	v_exp_f32_e32 v248, v248
	v_exp_f32_e32 v249, v249
	v_exp_f32_e32 v250, v250
	v_exp_f32_e32 v251, v251
	v_mul_f32_e32 v102, v102, v98
	v_mul_f32_e32 v103, v103, v99
	v_mul_f32_e32 v104, v104, v100
	v_mul_f32_e32 v105, v105, v101
	v_fma_f32 v248, v248, v235, v235
	v_fma_f32 v249, v249, v235, v235
	v_fma_f32 v250, v250, v235, v235
	v_fma_f32 v251, v251, v235, v235
	v_rcp_f32_e32 v248, v248
	v_rcp_f32_e32 v249, v249
	v_rcp_f32_e32 v250, v250
	v_rcp_f32_e32 v251, v251
	v_mul_f32_e32 v102, v102, v248
	v_mul_f32_e32 v103, v103, v249
	v_mul_f32_e32 v104, v104, v250
	v_mul_f32_e32 v105, v105, v251
	v_cvt_pk_bf16_f32 v108, v102, v103
	v_cvt_pk_bf16_f32 v109, v104, v105
	global_store_dwordx4 v176, v[106:109], s[22:23] offset:2048 sc1
	v_cvt_f32_i32_e32 v62, v62
	v_cvt_f32_i32_e32 v63, v63
	v_cvt_f32_i32_e32 v64, v64
	v_cvt_f32_i32_e32 v65, v65
	v_cvt_f32_i32_e32 v58, v58
	v_cvt_f32_i32_e32 v59, v59
	v_cvt_f32_i32_e32 v60, v60
	v_cvt_f32_i32_e32 v61, v61
	v_cvt_f32_i32_e32 v54, v54
	v_cvt_f32_i32_e32 v55, v55
	v_cvt_f32_i32_e32 v56, v56
	v_cvt_f32_i32_e32 v57, v57
	v_cvt_f32_i32_e32 v50, v50
	v_cvt_f32_i32_e32 v51, v51
	v_cvt_f32_i32_e32 v52, v52
	v_cvt_f32_i32_e32 v53, v53
	v_mul_f32_e32 v94, v94, v216
	v_mul_f32_e32 v95, v95, v217
	v_mul_f32_e32 v96, v96, v218
	v_mul_f32_e32 v97, v97, v219
	v_mul_f32_e32 v90, v90, v224
	v_mul_f32_e32 v91, v91, v225
	v_mul_f32_e32 v92, v92, v226
	v_mul_f32_e32 v93, v93, v227
	v_mul_f32_e32 v248, v94, v236
	v_mul_f32_e32 v249, v95, v236
	v_mul_f32_e32 v250, v96, v236
	v_mul_f32_e32 v251, v97, v236
	v_exp_f32_e32 v248, v248
	v_exp_f32_e32 v249, v249
	v_exp_f32_e32 v250, v250
	v_exp_f32_e32 v251, v251
	v_mul_f32_e32 v94, v94, v90
	v_mul_f32_e32 v95, v95, v91
	v_mul_f32_e32 v96, v96, v92
	v_mul_f32_e32 v97, v97, v93
	v_fma_f32 v248, v248, v237, v237
	v_fma_f32 v249, v249, v237, v237
	v_fma_f32 v250, v250, v237, v237
	v_fma_f32 v251, v251, v237, v237
	v_rcp_f32_e32 v248, v248
	v_rcp_f32_e32 v249, v249
	v_rcp_f32_e32 v250, v250
	v_rcp_f32_e32 v251, v251
	v_mul_f32_e32 v94, v94, v248
	v_mul_f32_e32 v95, v95, v249
	v_mul_f32_e32 v96, v96, v250
	v_mul_f32_e32 v97, v97, v251
	v_cvt_pk_bf16_f32 v90, v94, v95
	v_cvt_pk_bf16_f32 v91, v96, v97
	v_mul_f32_e32 v86, v86, v220
	v_mul_f32_e32 v87, v87, v221
	v_mul_f32_e32 v88, v88, v222
	v_mul_f32_e32 v89, v89, v223
	v_mul_f32_e32 v82, v82, v228
	v_mul_f32_e32 v83, v83, v229
	v_mul_f32_e32 v84, v84, v230
	v_mul_f32_e32 v85, v85, v231
	v_mul_f32_e32 v248, v86, v236
	v_mul_f32_e32 v249, v87, v236
	v_mul_f32_e32 v250, v88, v236
	v_mul_f32_e32 v251, v89, v236
	v_exp_f32_e32 v248, v248
	v_exp_f32_e32 v249, v249
	v_exp_f32_e32 v250, v250
	v_exp_f32_e32 v251, v251
	v_mul_f32_e32 v86, v86, v82
	v_mul_f32_e32 v87, v87, v83
	v_mul_f32_e32 v88, v88, v84
	v_mul_f32_e32 v89, v89, v85
	v_fma_f32 v248, v248, v237, v237
	v_fma_f32 v249, v249, v237, v237
	v_fma_f32 v250, v250, v237, v237
	v_fma_f32 v251, v251, v237, v237
	v_rcp_f32_e32 v248, v248
	v_rcp_f32_e32 v249, v249
	v_rcp_f32_e32 v250, v250
	v_rcp_f32_e32 v251, v251
	v_mul_f32_e32 v86, v86, v248
	v_mul_f32_e32 v87, v87, v249
	v_mul_f32_e32 v88, v88, v250
	v_mul_f32_e32 v89, v89, v251
	v_cvt_pk_bf16_f32 v92, v86, v87
	v_cvt_pk_bf16_f32 v93, v88, v89
	s_add_u32 s22, s20, 0x1000
	s_addc_u32 s23, s21, 0
	global_store_dwordx4 v176, v[90:93], s[22:23] sc1
	v_cvt_f32_i32_e32 v46, v46
	v_cvt_f32_i32_e32 v47, v47
	v_cvt_f32_i32_e32 v48, v48
	v_cvt_f32_i32_e32 v49, v49
	v_cvt_f32_i32_e32 v42, v42
	v_cvt_f32_i32_e32 v43, v43
	v_cvt_f32_i32_e32 v44, v44
	v_cvt_f32_i32_e32 v45, v45
	v_cvt_f32_i32_e32 v38, v38
	v_cvt_f32_i32_e32 v39, v39
	v_cvt_f32_i32_e32 v40, v40
	v_cvt_f32_i32_e32 v41, v41
	v_cvt_f32_i32_e32 v34, v34
	v_cvt_f32_i32_e32 v35, v35
	v_cvt_f32_i32_e32 v36, v36
	v_cvt_f32_i32_e32 v37, v37
	v_mul_f32_e32 v78, v78, v216
	v_mul_f32_e32 v79, v79, v217
	v_mul_f32_e32 v80, v80, v218
	v_mul_f32_e32 v81, v81, v219
	v_mul_f32_e32 v74, v74, v224
	v_mul_f32_e32 v75, v75, v225
; __device__ __forceinline__ float silu_f(float x) { return x * __builtin_amdgcn_rcpf(1.0f + __builtin_amdgcn_exp2f(-1.4426950408889634f * x)); }
;     __device__ __forceinline__ void operator()(const i32x4 (&acc)[2][2][4][2], const pg8::Unit& u, int wr, int wc, int fr_, int fq_, int tid) {
;     ...
;         for (int ai = 0; ai < 2; ++ai)
; #pragma unroll
;             for (int m = 0; m < 4; ++m) {
;                 const int row = row0 + ai * 128 + m * 16;
;                 const float rs = rsl[wr * 64 + fr + ai * 128 + m * 16];
;                 f32x4 h[2];
; #pragma unroll
;                 for (int n = 0; n < 2; ++n) {
; #pragma unroll
;                     for (int i = 0; i < 4; ++i) { const float g = (float)acc[ai][0][m][n][i] * (rs * cs[0][n][i]), up = (float)acc[ai][1][m][n][i] * (rs * cs[1][n][i]); h[n][i] = silu_f(g) * up; } }
;                 *(u32x4*)(H + ((size_t)(u.pm * (DFF / 64) + (col0 >> 6)) * 256 + (size_t)(row & 255)) * 64 + (col0 & 63)) = pack8bf(h[0], h[1]);
;             }
	v_mul_f32_e32 v76, v76, v226
	v_mul_f32_e32 v77, v77, v227
	v_mul_f32_e32 v248, v78, v238
	v_mul_f32_e32 v249, v79, v238
	v_mul_f32_e32 v250, v80, v238
	v_mul_f32_e32 v251, v81, v238
	v_exp_f32_e32 v248, v248
	v_exp_f32_e32 v249, v249
	v_exp_f32_e32 v250, v250
	v_exp_f32_e32 v251, v251
	v_mul_f32_e32 v78, v78, v74
	v_mul_f32_e32 v79, v79, v75
	v_mul_f32_e32 v80, v80, v76
	v_mul_f32_e32 v81, v81, v77
	v_fma_f32 v248, v248, v239, v239
	v_fma_f32 v249, v249, v239, v239
	v_fma_f32 v250, v250, v239, v239
	v_fma_f32 v251, v251, v239, v239
	v_rcp_f32_e32 v248, v248
	v_rcp_f32_e32 v249, v249
	v_rcp_f32_e32 v250, v250
	v_rcp_f32_e32 v251, v251
	v_mul_f32_e32 v78, v78, v248
	v_mul_f32_e32 v79, v79, v249
	v_mul_f32_e32 v80, v80, v250
	v_mul_f32_e32 v81, v81, v251
	v_cvt_pk_bf16_f32 v74, v78, v79
	v_cvt_pk_bf16_f32 v75, v80, v81
	v_mul_f32_e32 v70, v70, v220
	v_mul_f32_e32 v71, v71, v221
	v_mul_f32_e32 v72, v72, v222
	v_mul_f32_e32 v73, v73, v223
	v_mul_f32_e32 v66, v66, v228
	v_mul_f32_e32 v67, v67, v229
	v_mul_f32_e32 v68, v68, v230
	v_mul_f32_e32 v69, v69, v231
	v_mul_f32_e32 v248, v70, v238
	v_mul_f32_e32 v249, v71, v238
	v_mul_f32_e32 v250, v72, v238
	v_mul_f32_e32 v251, v73, v238
	v_exp_f32_e32 v248, v248
	v_exp_f32_e32 v249, v249
	v_exp_f32_e32 v250, v250
	v_exp_f32_e32 v251, v251
	v_mul_f32_e32 v70, v70, v66
	v_mul_f32_e32 v71, v71, v67
	v_mul_f32_e32 v72, v72, v68
	v_mul_f32_e32 v73, v73, v69
	v_fma_f32 v248, v248, v239, v239
	v_fma_f32 v249, v249, v239, v239
	v_fma_f32 v250, v250, v239, v239
	v_fma_f32 v251, v251, v239, v239
	v_rcp_f32_e32 v248, v248
	v_rcp_f32_e32 v249, v249
	v_rcp_f32_e32 v250, v250
	v_rcp_f32_e32 v251, v251
	v_mul_f32_e32 v70, v70, v248
	v_mul_f32_e32 v71, v71, v249
	v_mul_f32_e32 v72, v72, v250
	v_mul_f32_e32 v73, v73, v251
	v_cvt_pk_bf16_f32 v76, v70, v71
	v_cvt_pk_bf16_f32 v77, v72, v73
	global_store_dwordx4 v176, v[74:77], s[22:23] offset:2048 sc1
	v_cvt_f32_i32_e32 v30, v30
	v_cvt_f32_i32_e32 v31, v31
	v_cvt_f32_i32_e32 v32, v32
	v_cvt_f32_i32_e32 v33, v33
	v_cvt_f32_i32_e32 v26, v26
	v_cvt_f32_i32_e32 v27, v27
	v_cvt_f32_i32_e32 v28, v28
	v_cvt_f32_i32_e32 v29, v29
	v_cvt_f32_i32_e32 v22, v22
	v_cvt_f32_i32_e32 v23, v23
	v_cvt_f32_i32_e32 v24, v24
	v_cvt_f32_i32_e32 v25, v25
	v_cvt_f32_i32_e32 v18, v18
	v_cvt_f32_i32_e32 v19, v19
	v_cvt_f32_i32_e32 v20, v20
	v_cvt_f32_i32_e32 v21, v21
	v_mul_f32_e32 v62, v62, v216
	v_mul_f32_e32 v63, v63, v217
	v_mul_f32_e32 v64, v64, v218
	v_mul_f32_e32 v65, v65, v219
	v_mul_f32_e32 v58, v58, v224
	v_mul_f32_e32 v59, v59, v225
	v_mul_f32_e32 v60, v60, v226
	v_mul_f32_e32 v61, v61, v227
	v_mul_f32_e32 v248, v62, v240
	v_mul_f32_e32 v249, v63, v240
	v_mul_f32_e32 v250, v64, v240
	v_mul_f32_e32 v251, v65, v240
	v_exp_f32_e32 v248, v248
	v_exp_f32_e32 v249, v249
	v_exp_f32_e32 v250, v250
	v_exp_f32_e32 v251, v251
	v_mul_f32_e32 v62, v62, v58
	v_mul_f32_e32 v63, v63, v59
	v_mul_f32_e32 v64, v64, v60
	v_mul_f32_e32 v65, v65, v61
	v_fma_f32 v248, v248, v241, v241
	v_fma_f32 v249, v249, v241, v241
	v_fma_f32 v250, v250, v241, v241
	v_fma_f32 v251, v251, v241, v241
	v_rcp_f32_e32 v248, v248
	v_rcp_f32_e32 v249, v249
	v_rcp_f32_e32 v250, v250
	v_rcp_f32_e32 v251, v251
	v_mul_f32_e32 v62, v62, v248
	v_mul_f32_e32 v63, v63, v249
	v_mul_f32_e32 v64, v64, v250
	v_mul_f32_e32 v65, v65, v251
	v_cvt_pk_bf16_f32 v58, v62, v63
	v_cvt_pk_bf16_f32 v59, v64, v65
	v_mul_f32_e32 v54, v54, v220
	v_mul_f32_e32 v55, v55, v221
	v_mul_f32_e32 v56, v56, v222
	v_mul_f32_e32 v57, v57, v223
	v_mul_f32_e32 v50, v50, v228
	v_mul_f32_e32 v51, v51, v229
	v_mul_f32_e32 v52, v52, v230
	v_mul_f32_e32 v53, v53, v231
	v_mul_f32_e32 v248, v54, v240
	v_mul_f32_e32 v249, v55, v240
	v_mul_f32_e32 v250, v56, v240
	v_mul_f32_e32 v251, v57, v240
	v_exp_f32_e32 v248, v248
	v_exp_f32_e32 v249, v249
	v_exp_f32_e32 v250, v250
	v_exp_f32_e32 v251, v251
	v_mul_f32_e32 v54, v54, v50
	v_mul_f32_e32 v55, v55, v51
	v_mul_f32_e32 v56, v56, v52
	v_mul_f32_e32 v57, v57, v53
	v_fma_f32 v248, v248, v241, v241
	v_fma_f32 v249, v249, v241, v241
	v_fma_f32 v250, v250, v241, v241
	v_fma_f32 v251, v251, v241, v241
	v_rcp_f32_e32 v248, v248
	v_rcp_f32_e32 v249, v249
	v_rcp_f32_e32 v250, v250
	v_rcp_f32_e32 v251, v251
	v_mul_f32_e32 v54, v54, v248
	v_mul_f32_e32 v55, v55, v249
	v_mul_f32_e32 v56, v56, v250
	v_mul_f32_e32 v57, v57, v251
	v_cvt_pk_bf16_f32 v60, v54, v55
	v_cvt_pk_bf16_f32 v61, v56, v57
	s_add_u32 s22, s20, 0x4000
	s_addc_u32 s23, s21, 0
	global_store_dwordx4 v176, v[58:61], s[22:23] sc1
	v_cvt_f32_i32_e32 v14, v14
	v_cvt_f32_i32_e32 v15, v15
	v_cvt_f32_i32_e32 v16, v16
	v_cvt_f32_i32_e32 v17, v17
	v_cvt_f32_i32_e32 v10, v10
	v_cvt_f32_i32_e32 v11, v11
	v_cvt_f32_i32_e32 v12, v12
	v_cvt_f32_i32_e32 v13, v13
	v_cvt_f32_i32_e32 v6, v6
	v_cvt_f32_i32_e32 v7, v7
	v_cvt_f32_i32_e32 v8, v8
	v_cvt_f32_i32_e32 v9, v9
	v_cvt_f32_i32_e32 v2, v2
	v_cvt_f32_i32_e32 v3, v3
	v_cvt_f32_i32_e32 v4, v4
	v_cvt_f32_i32_e32 v5, v5
	v_mul_f32_e32 v46, v46, v216
	v_mul_f32_e32 v47, v47, v217
	v_mul_f32_e32 v48, v48, v218
	v_mul_f32_e32 v49, v49, v219
	v_mul_f32_e32 v42, v42, v224
	v_mul_f32_e32 v43, v43, v225
	v_mul_f32_e32 v44, v44, v226
	v_mul_f32_e32 v45, v45, v227
	v_mul_f32_e32 v248, v46, v242
	v_mul_f32_e32 v249, v47, v242
	v_mul_f32_e32 v250, v48, v242
	v_mul_f32_e32 v251, v49, v242
	v_exp_f32_e32 v248, v248
	v_exp_f32_e32 v249, v249
	v_exp_f32_e32 v250, v250
	v_exp_f32_e32 v251, v251
	v_mul_f32_e32 v46, v46, v42
	v_mul_f32_e32 v47, v47, v43
	v_mul_f32_e32 v48, v48, v44
	v_mul_f32_e32 v49, v49, v45
	v_fma_f32 v248, v248, v243, v243
	v_fma_f32 v249, v249, v243, v243
	v_fma_f32 v250, v250, v243, v243
	v_fma_f32 v251, v251, v243, v243
	v_rcp_f32_e32 v248, v248
; __device__ __forceinline__ float silu_f(float x) { return x * __builtin_amdgcn_rcpf(1.0f + __builtin_amdgcn_exp2f(-1.4426950408889634f * x)); }
; #define PG8_BAR __builtin_amdgcn_s_barrier()
;     ...
;         if constexpr (ALIGN_EPI) { if (wr == 0) PG8_BAR; }
;         E(acc, cur, wr, wc, fr, fq, tid); S.done(cur);
;         if (!has_next) break;
;     __device__ __forceinline__ void operator()(const i32x4 (&acc)[2][2][4][2], const pg8::Unit& u, int wr, int wc, int fr_, int fq_, int tid) {
;     ...
;         for (int ai = 0; ai < 2; ++ai)
; #pragma unroll
;             for (int m = 0; m < 4; ++m) {
;                 const int row = row0 + ai * 128 + m * 16;
;                 const float rs = rsl[wr * 64 + fr + ai * 128 + m * 16];
;                 f32x4 h[2];
; #pragma unroll
;                 for (int n = 0; n < 2; ++n) {
; #pragma unroll
;                     for (int i = 0; i < 4; ++i) { const float g = (float)acc[ai][0][m][n][i] * (rs * cs[0][n][i]), up = (float)acc[ai][1][m][n][i] * (rs * cs[1][n][i]); h[n][i] = silu_f(g) * up; } }
;                 *(u32x4*)(H + ((size_t)(u.pm * (DFF / 64) + (col0 >> 6)) * 256 + (size_t)(row & 255)) * 64 + (col0 & 63)) = pack8bf(h[0], h[1]);
;             }
	v_rcp_f32_e32 v249, v249
	v_rcp_f32_e32 v250, v250
	v_rcp_f32_e32 v251, v251
	v_mul_f32_e32 v46, v46, v248
	v_mul_f32_e32 v47, v47, v249
	v_mul_f32_e32 v48, v48, v250
	v_mul_f32_e32 v49, v49, v251
	v_cvt_pk_bf16_f32 v42, v46, v47
	v_cvt_pk_bf16_f32 v43, v48, v49
	v_mul_f32_e32 v38, v38, v220
	v_mul_f32_e32 v39, v39, v221
	v_mul_f32_e32 v40, v40, v222
	v_mul_f32_e32 v41, v41, v223
	v_mul_f32_e32 v34, v34, v228
	v_mul_f32_e32 v35, v35, v229
	v_mul_f32_e32 v36, v36, v230
	v_mul_f32_e32 v37, v37, v231
	v_mul_f32_e32 v248, v38, v242
	v_mul_f32_e32 v249, v39, v242
	v_mul_f32_e32 v250, v40, v242
	v_mul_f32_e32 v251, v41, v242
	v_exp_f32_e32 v248, v248
	v_exp_f32_e32 v249, v249
	v_exp_f32_e32 v250, v250
	v_exp_f32_e32 v251, v251
	v_mul_f32_e32 v38, v38, v34
	v_mul_f32_e32 v39, v39, v35
	v_mul_f32_e32 v40, v40, v36
	v_mul_f32_e32 v41, v41, v37
	v_fma_f32 v248, v248, v243, v243
	v_fma_f32 v249, v249, v243, v243
	v_fma_f32 v250, v250, v243, v243
	v_fma_f32 v251, v251, v243, v243
	v_rcp_f32_e32 v248, v248
	v_rcp_f32_e32 v249, v249
	v_rcp_f32_e32 v250, v250
	v_rcp_f32_e32 v251, v251
	v_mul_f32_e32 v38, v38, v248
	v_mul_f32_e32 v39, v39, v249
	v_mul_f32_e32 v40, v40, v250
	v_mul_f32_e32 v41, v41, v251
	v_cvt_pk_bf16_f32 v44, v38, v39
	v_cvt_pk_bf16_f32 v45, v40, v41
	global_store_dwordx4 v176, v[42:45], s[22:23] offset:2048 sc1
	v_mul_f32_e32 v30, v30, v216
	v_mul_f32_e32 v31, v31, v217
	v_mul_f32_e32 v32, v32, v218
	v_mul_f32_e32 v33, v33, v219
	v_mul_f32_e32 v26, v26, v224
	v_mul_f32_e32 v27, v27, v225
	v_mul_f32_e32 v28, v28, v226
	v_mul_f32_e32 v29, v29, v227
	v_mul_f32_e32 v248, v30, v244
	v_mul_f32_e32 v249, v31, v244
	v_mul_f32_e32 v250, v32, v244
	v_mul_f32_e32 v251, v33, v244
	v_exp_f32_e32 v248, v248
	v_exp_f32_e32 v249, v249
	v_exp_f32_e32 v250, v250
	v_exp_f32_e32 v251, v251
	v_mul_f32_e32 v30, v30, v26
	v_mul_f32_e32 v31, v31, v27
	v_mul_f32_e32 v32, v32, v28
	v_mul_f32_e32 v33, v33, v29
	v_fma_f32 v248, v248, v245, v245
	v_fma_f32 v249, v249, v245, v245
	v_fma_f32 v250, v250, v245, v245
	v_fma_f32 v251, v251, v245, v245
	v_rcp_f32_e32 v248, v248
	v_rcp_f32_e32 v249, v249
	v_rcp_f32_e32 v250, v250
	v_rcp_f32_e32 v251, v251
	v_mul_f32_e32 v30, v30, v248
	v_mul_f32_e32 v31, v31, v249
	v_mul_f32_e32 v32, v32, v250
	v_mul_f32_e32 v33, v33, v251
	v_cvt_pk_bf16_f32 v26, v30, v31
	v_cvt_pk_bf16_f32 v27, v32, v33
	v_mul_f32_e32 v22, v22, v220
	v_mul_f32_e32 v23, v23, v221
	v_mul_f32_e32 v24, v24, v222
	v_mul_f32_e32 v25, v25, v223
	v_mul_f32_e32 v18, v18, v228
	v_mul_f32_e32 v19, v19, v229
	v_mul_f32_e32 v20, v20, v230
	v_mul_f32_e32 v21, v21, v231
	v_mul_f32_e32 v248, v22, v244
	v_mul_f32_e32 v249, v23, v244
	v_mul_f32_e32 v250, v24, v244
	v_mul_f32_e32 v251, v25, v244
	v_exp_f32_e32 v248, v248
	v_exp_f32_e32 v249, v249
	v_exp_f32_e32 v250, v250
	v_exp_f32_e32 v251, v251
	v_mul_f32_e32 v22, v22, v18
	v_mul_f32_e32 v23, v23, v19
	v_mul_f32_e32 v24, v24, v20
	v_mul_f32_e32 v25, v25, v21
	v_fma_f32 v248, v248, v245, v245
	v_fma_f32 v249, v249, v245, v245
	v_fma_f32 v250, v250, v245, v245
	v_fma_f32 v251, v251, v245, v245
	v_rcp_f32_e32 v248, v248
	v_rcp_f32_e32 v249, v249
	v_rcp_f32_e32 v250, v250
	v_rcp_f32_e32 v251, v251
	v_mul_f32_e32 v22, v22, v248
	v_mul_f32_e32 v23, v23, v249
	v_mul_f32_e32 v24, v24, v250
	v_mul_f32_e32 v25, v25, v251
	v_cvt_pk_bf16_f32 v28, v22, v23
	v_cvt_pk_bf16_f32 v29, v24, v25
	s_add_u32 s22, s20, 0x5000
	s_addc_u32 s23, s21, 0
	global_store_dwordx4 v176, v[26:29], s[22:23] sc1
	v_mul_f32_e32 v14, v14, v216
	v_mul_f32_e32 v15, v15, v217
	v_mul_f32_e32 v16, v16, v218
	v_mul_f32_e32 v17, v17, v219
	v_mul_f32_e32 v10, v10, v224
	v_mul_f32_e32 v11, v11, v225
	v_mul_f32_e32 v12, v12, v226
	v_mul_f32_e32 v13, v13, v227
	v_mul_f32_e32 v248, v14, v246
	v_mul_f32_e32 v249, v15, v246
	v_mul_f32_e32 v250, v16, v246
	v_mul_f32_e32 v251, v17, v246
	v_exp_f32_e32 v248, v248
	v_exp_f32_e32 v249, v249
	v_exp_f32_e32 v250, v250
	v_exp_f32_e32 v251, v251
	v_mul_f32_e32 v14, v14, v10
	v_mul_f32_e32 v15, v15, v11
	v_mul_f32_e32 v16, v16, v12
	v_mul_f32_e32 v17, v17, v13
	v_fma_f32 v248, v248, v247, v247
	v_fma_f32 v249, v249, v247, v247
	v_fma_f32 v250, v250, v247, v247
	v_fma_f32 v251, v251, v247, v247
	v_rcp_f32_e32 v248, v248
	v_rcp_f32_e32 v249, v249
	v_rcp_f32_e32 v250, v250
	v_rcp_f32_e32 v251, v251
	v_mul_f32_e32 v14, v14, v248
	v_mul_f32_e32 v15, v15, v249
	v_mul_f32_e32 v16, v16, v250
	v_mul_f32_e32 v17, v17, v251
	v_cvt_pk_bf16_f32 v10, v14, v15
	v_cvt_pk_bf16_f32 v11, v16, v17
	v_mul_f32_e32 v6, v6, v220
	v_mul_f32_e32 v7, v7, v221
	v_mul_f32_e32 v8, v8, v222
	v_mul_f32_e32 v9, v9, v223
	v_mul_f32_e32 v2, v2, v228
	v_mul_f32_e32 v3, v3, v229
	v_mul_f32_e32 v4, v4, v230
	v_mul_f32_e32 v5, v5, v231
	v_mul_f32_e32 v248, v6, v246
	v_mul_f32_e32 v249, v7, v246
	v_mul_f32_e32 v250, v8, v246
	v_mul_f32_e32 v251, v9, v246
	v_exp_f32_e32 v248, v248
	v_exp_f32_e32 v249, v249
	v_exp_f32_e32 v250, v250
	v_exp_f32_e32 v251, v251
	v_mul_f32_e32 v6, v6, v2
	v_mul_f32_e32 v7, v7, v3
	v_mul_f32_e32 v8, v8, v4
	v_mul_f32_e32 v9, v9, v5
	v_fma_f32 v248, v248, v247, v247
	v_fma_f32 v249, v249, v247, v247
	v_fma_f32 v250, v250, v247, v247
	v_fma_f32 v251, v251, v247, v247
	v_rcp_f32_e32 v248, v248
	v_rcp_f32_e32 v249, v249
	v_rcp_f32_e32 v250, v250
	v_rcp_f32_e32 v251, v251
	v_mul_f32_e32 v6, v6, v248
	v_mul_f32_e32 v7, v7, v249
	v_mul_f32_e32 v8, v8, v250
	v_mul_f32_e32 v9, v9, v251
	v_cvt_pk_bf16_f32 v12, v6, v7
	v_cvt_pk_bf16_f32 v13, v8, v9
	global_store_dwordx4 v176, v[10:13], s[22:23] offset:2048 sc1
	s_mov_b64 s[20:21], -1
	s_andn2_b64 vcc, exec, s[4:5]
	s_cbranch_vccnz .LBB0_159
	s_andn2_b64 vcc, exec, s[6:7]
	s_cbranch_vccnz .LBB0_158
	s_barrier
	s_branch .LBB0_158
